# barrier spin loops poll every ~512 cycles (s_sleep 8 instead of 1): fewer polls on the fabric while the last workgroups still run; on v068
# speedup vs baseline: 1.0124x; 1.0124x over previous
.LBB0_109:
	s_sleep 8
	global_load_dword v2, v0, s[4:5] offset:32 sc1
	s_waitcnt vmcnt(0)
	v_and_b32_e32 v2, 0xffff0000, v2
	v_cmp_ne_u32_e32 vcc, v2, v1
	s_or_b64 s[6:7], vcc, s[6:7]
	s_andn2_b64 exec, exec, s[6:7]
	s_cbranch_execnz .LBB0_109

.LBB0_138:
	global_load_dword v15, v16, s[6:7] sc1
	s_waitcnt lgkmcnt(0)
	global_load_dword v0, v16, s[8:9] sc1
	global_load_dword v1, v16, s[10:11] sc1
	global_load_dword v2, v16, s[14:15] sc1
	global_load_dword v3, v16, s[16:17] sc1
	global_load_dword v4, v16, s[18:19] sc1
	global_load_dword v5, v16, s[20:21] sc1
	global_load_dword v6, v16, s[22:23] sc1
	global_load_dword v7, v16, s[26:27] sc1
	global_load_dword v8, v16, s[28:29] sc1
	global_load_dword v9, v16, s[40:41] sc1
	global_load_dword v10, v16, s[42:43] sc1
	global_load_dword v11, v16, s[48:49] sc1
	global_load_dword v12, v16, s[50:51] sc1
	global_load_dword v13, v16, s[52:53] sc1
	global_load_dword v14, v16, s[54:55] sc1
	s_mov_b64 s[56:57], -1
	s_mov_b64 s[58:59], -1
	s_waitcnt vmcnt(14)
	v_add_u32_e32 v17, v0, v15
	s_waitcnt vmcnt(13)
	v_add_u32_e32 v17, v17, v1
	s_waitcnt vmcnt(12)
	v_add_u32_e32 v17, v17, v2
	s_waitcnt vmcnt(11)
	v_add_u32_e32 v17, v17, v3
	s_waitcnt vmcnt(10)
	v_add_u32_e32 v17, v17, v4
	s_waitcnt vmcnt(9)
	v_add_u32_e32 v17, v17, v5
	s_waitcnt vmcnt(8)
	v_add_u32_e32 v17, v17, v6
	s_waitcnt vmcnt(7)
	v_add_u32_e32 v17, v17, v7
	s_waitcnt vmcnt(6)
	v_add_u32_e32 v17, v17, v8
	s_waitcnt vmcnt(5)
	v_add_u32_e32 v17, v17, v9
	s_waitcnt vmcnt(4)
	v_add_u32_e32 v17, v17, v10
	s_waitcnt vmcnt(3)
	v_add_u32_e32 v17, v17, v11
	s_waitcnt vmcnt(2)
	v_add_u32_e32 v17, v17, v12
	s_waitcnt vmcnt(1)
	v_add_u32_e32 v17, v17, v13
	s_waitcnt vmcnt(0)
	v_add_u32_e32 v17, v17, v14
	v_cmp_eq_u32_e32 vcc, s3, v17
	s_cbranch_vccnz .LBB0_137
	s_and_b32 s13, s12, 0xff
	s_cmp_eq_u32 s13, 0
	s_mov_b64 s[62:63], -1
	s_sleep 8
	s_cbranch_scc0 .LBB0_142
	global_load_dword v17, v16, s[4:5] sc1
	s_waitcnt vmcnt(0)
	v_cmp_eq_u32_e32 vcc, 0, v17
	s_cbranch_vccnz .LBB0_144
	s_mov_b64 s[62:63], 0

.LBB0_156:
	s_and_b32 s12, s3, 0xff
	s_mov_b64 s[20:21], -1
	s_cmp_lg_u32 s12, 0
	s_mov_b64 s[26:27], -1
	s_sleep 8
	s_cbranch_scc1 .LBB0_159
	global_load_dword v2, v0, s[10:11] sc1
	s_waitcnt vmcnt(0)
	v_cmp_eq_u32_e32 vcc, 0, v2
	s_cbranch_vccnz .LBB0_161
	s_mov_b64 s[26:27], 0
	s_mov_b64 s[22:23], -1

.LBB0_173:
	s_and_b32 s12, s3, 0xff
	s_cmp_lg_u32 s12, 0
	s_mov_b64 s[22:23], -1
	s_sleep 8
	s_cbranch_scc1 .LBB0_176
	global_load_dword v1, v0, s[10:11] sc1
	s_waitcnt vmcnt(0)
	v_cmp_eq_u32_e32 vcc, 0, v1
	s_cbranch_vccnz .LBB0_178
	s_mov_b64 s[22:23], 0
	s_mov_b64 s[20:21], -1

.LBB0_254:
	global_load_dword v15, v16, s[6:7] sc1
	s_waitcnt lgkmcnt(0)
	global_load_dword v0, v16, s[8:9] sc1
	global_load_dword v1, v16, s[10:11] sc1
	global_load_dword v2, v16, s[20:21] sc1
	global_load_dword v3, v16, s[22:23] sc1
	global_load_dword v4, v16, s[26:27] sc1
	global_load_dword v5, v16, s[28:29] sc1
	global_load_dword v6, v16, s[40:41] sc1
	global_load_dword v7, v16, s[42:43] sc1
	global_load_dword v8, v16, s[48:49] sc1
	global_load_dword v9, v16, s[50:51] sc1
	global_load_dword v10, v16, s[52:53] sc1
	global_load_dword v11, v16, s[54:55] sc1
	global_load_dword v12, v16, s[56:57] sc1
	global_load_dword v13, v16, s[58:59] sc1
	global_load_dword v14, v16, s[62:63] sc1
	s_mov_b64 s[64:65], -1
	s_mov_b64 s[66:67], -1
	s_waitcnt vmcnt(14)
	v_add_u32_e32 v17, v0, v15
	s_waitcnt vmcnt(13)
	v_add_u32_e32 v17, v17, v1
	s_waitcnt vmcnt(12)
	v_add_u32_e32 v17, v17, v2
	s_waitcnt vmcnt(11)
	v_add_u32_e32 v17, v17, v3
	s_waitcnt vmcnt(10)
	v_add_u32_e32 v17, v17, v4
	s_waitcnt vmcnt(9)
	v_add_u32_e32 v17, v17, v5
	s_waitcnt vmcnt(8)
	v_add_u32_e32 v17, v17, v6
	s_waitcnt vmcnt(7)
	v_add_u32_e32 v17, v17, v7
	s_waitcnt vmcnt(6)
	v_add_u32_e32 v17, v17, v8
	s_waitcnt vmcnt(5)
	v_add_u32_e32 v17, v17, v9
	s_waitcnt vmcnt(4)
	v_add_u32_e32 v17, v17, v10
	s_waitcnt vmcnt(3)
	v_add_u32_e32 v17, v17, v11
	s_waitcnt vmcnt(2)
	v_add_u32_e32 v17, v17, v12
	s_waitcnt vmcnt(1)
	v_add_u32_e32 v17, v17, v13
	s_waitcnt vmcnt(0)
	v_add_u32_e32 v17, v17, v14
	v_cmp_eq_u32_e32 vcc, s3, v17
	s_cbranch_vccnz .LBB0_253
	s_and_b32 s13, s12, 0xff
	s_cmp_eq_u32 s13, 0
	s_mov_b64 s[82:83], -1
	s_sleep 8
	s_cbranch_scc0 .LBB0_258
	global_load_dword v17, v16, s[4:5] sc1
	s_waitcnt vmcnt(0)
	v_cmp_eq_u32_e32 vcc, 0, v17
	s_cbranch_vccnz .LBB0_260
	s_mov_b64 s[82:83], 0

.LBB0_272:
	s_and_b32 s12, s3, 0xff
	s_mov_b64 s[28:29], -1
	s_cmp_lg_u32 s12, 0
	s_mov_b64 s[42:43], -1
	s_sleep 8
	s_cbranch_scc1 .LBB0_275
	global_load_dword v2, v0, s[10:11] sc1
	s_waitcnt vmcnt(0)
	v_cmp_eq_u32_e32 vcc, 0, v2
	s_cbranch_vccnz .LBB0_277
	s_mov_b64 s[42:43], 0
	s_mov_b64 s[40:41], -1

.LBB0_289:
	s_and_b32 s12, s3, 0xff
	s_cmp_lg_u32 s12, 0
	s_mov_b64 s[40:41], -1
	s_sleep 8
	s_cbranch_scc1 .LBB0_292
	global_load_dword v1, v0, s[10:11] sc1
	s_waitcnt vmcnt(0)
	v_cmp_eq_u32_e32 vcc, 0, v1
	s_cbranch_vccnz .LBB0_294
	s_mov_b64 s[40:41], 0
	s_mov_b64 s[28:29], -1

.LBB0_316:
	global_load_dword v15, v16, s[6:7] sc1
	s_waitcnt lgkmcnt(0)
	global_load_dword v0, v16, s[8:9] sc1
	global_load_dword v1, v16, s[10:11] sc1
	global_load_dword v2, v16, s[22:23] sc1
	global_load_dword v3, v16, s[26:27] sc1
	global_load_dword v4, v16, s[28:29] sc1
	global_load_dword v5, v16, s[40:41] sc1
	global_load_dword v6, v16, s[42:43] sc1
	global_load_dword v7, v16, s[48:49] sc1
	global_load_dword v8, v16, s[50:51] sc1
	global_load_dword v9, v16, s[52:53] sc1
	global_load_dword v10, v16, s[54:55] sc1
	global_load_dword v11, v16, s[56:57] sc1
	global_load_dword v12, v16, s[58:59] sc1
	global_load_dword v13, v16, s[62:63] sc1
	global_load_dword v14, v16, s[64:65] sc1
	s_mov_b64 s[66:67], -1
	s_mov_b64 s[82:83], -1
	s_waitcnt vmcnt(14)
	v_add_u32_e32 v17, v0, v15
	s_waitcnt vmcnt(13)
	v_add_u32_e32 v17, v17, v1
	s_waitcnt vmcnt(12)
	v_add_u32_e32 v17, v17, v2
	s_waitcnt vmcnt(11)
	v_add_u32_e32 v17, v17, v3
	s_waitcnt vmcnt(10)
	v_add_u32_e32 v17, v17, v4
	s_waitcnt vmcnt(9)
	v_add_u32_e32 v17, v17, v5
	s_waitcnt vmcnt(8)
	v_add_u32_e32 v17, v17, v6
	s_waitcnt vmcnt(7)
	v_add_u32_e32 v17, v17, v7
	s_waitcnt vmcnt(6)
	v_add_u32_e32 v17, v17, v8
	s_waitcnt vmcnt(5)
	v_add_u32_e32 v17, v17, v9
	s_waitcnt vmcnt(4)
	v_add_u32_e32 v17, v17, v10
	s_waitcnt vmcnt(3)
	v_add_u32_e32 v17, v17, v11
	s_waitcnt vmcnt(2)
	v_add_u32_e32 v17, v17, v12
	s_waitcnt vmcnt(1)
	v_add_u32_e32 v17, v17, v13
	s_waitcnt vmcnt(0)
	v_add_u32_e32 v17, v17, v14
	v_cmp_eq_u32_e32 vcc, s3, v17
	s_cbranch_vccnz .LBB0_315
	s_and_b32 s13, s12, 0xff
	s_cmp_eq_u32 s13, 0
	s_mov_b64 s[84:85], -1
	s_sleep 8
	s_cbranch_scc0 .LBB0_320
	global_load_dword v17, v16, s[4:5] sc1
	s_waitcnt vmcnt(0)
	v_cmp_eq_u32_e32 vcc, 0, v17
	s_cbranch_vccnz .LBB0_322
	s_mov_b64 s[84:85], 0

.LBB0_334:
	s_and_b32 s12, s3, 0xff
	s_mov_b64 s[40:41], -1
	s_cmp_lg_u32 s12, 0
	s_mov_b64 s[48:49], -1
	s_sleep 8
	s_cbranch_scc1 .LBB0_337
	global_load_dword v2, v0, s[10:11] sc1
	s_waitcnt vmcnt(0)
	v_cmp_eq_u32_e32 vcc, 0, v2
	s_cbranch_vccnz .LBB0_339
	s_mov_b64 s[48:49], 0
	s_mov_b64 s[42:43], -1

.LBB0_351:
	s_and_b32 s12, s3, 0xff
	s_cmp_lg_u32 s12, 0
	s_mov_b64 s[42:43], -1
	s_sleep 8
	s_cbranch_scc1 .LBB0_354
	global_load_dword v1, v0, s[10:11] sc1
	s_waitcnt vmcnt(0)
	v_cmp_eq_u32_e32 vcc, 0, v1
	s_cbranch_vccnz .LBB0_356
	s_mov_b64 s[42:43], 0
	s_mov_b64 s[40:41], -1

.LBB0_899:
	global_load_dword v15, v16, s[6:7] sc1
	s_waitcnt lgkmcnt(0)
	global_load_dword v0, v16, s[8:9] sc1
	global_load_dword v1, v16, s[10:11] sc1
	global_load_dword v2, v16, s[22:23] sc1
	global_load_dword v3, v16, s[26:27] sc1
	global_load_dword v4, v16, s[28:29] sc1
	global_load_dword v5, v16, s[30:31] sc1
	global_load_dword v6, v16, s[36:37] sc1
	global_load_dword v7, v16, s[38:39] sc1
	global_load_dword v8, v16, s[40:41] sc1
	global_load_dword v9, v16, s[42:43] sc1
	global_load_dword v10, v16, s[48:49] sc1
	global_load_dword v11, v16, s[50:51] sc1
	global_load_dword v12, v16, s[52:53] sc1
	global_load_dword v13, v16, s[54:55] sc1
	global_load_dword v14, v16, s[56:57] sc1
	s_mov_b64 s[58:59], -1
	s_mov_b64 s[62:63], -1
	s_waitcnt vmcnt(14)
	v_add_u32_e32 v17, v0, v15
	s_waitcnt vmcnt(13)
	v_add_u32_e32 v17, v17, v1
	s_waitcnt vmcnt(12)
	v_add_u32_e32 v17, v17, v2
	s_waitcnt vmcnt(11)
	v_add_u32_e32 v17, v17, v3
	s_waitcnt vmcnt(10)
	v_add_u32_e32 v17, v17, v4
	s_waitcnt vmcnt(9)
	v_add_u32_e32 v17, v17, v5
	s_waitcnt vmcnt(8)
	v_add_u32_e32 v17, v17, v6
	s_waitcnt vmcnt(7)
	v_add_u32_e32 v17, v17, v7
	s_waitcnt vmcnt(6)
	v_add_u32_e32 v17, v17, v8
	s_waitcnt vmcnt(5)
	v_add_u32_e32 v17, v17, v9
	s_waitcnt vmcnt(4)
	v_add_u32_e32 v17, v17, v10
	s_waitcnt vmcnt(3)
	v_add_u32_e32 v17, v17, v11
	s_waitcnt vmcnt(2)
	v_add_u32_e32 v17, v17, v12
	s_waitcnt vmcnt(1)
	v_add_u32_e32 v17, v17, v13
	s_waitcnt vmcnt(0)
	v_add_u32_e32 v17, v17, v14
	v_cmp_eq_u32_e32 vcc, s3, v17
	s_cbranch_vccnz .LBB0_898
	s_and_b32 s13, s12, 0xff
	s_cmp_eq_u32 s13, 0
	s_mov_b64 s[64:65], -1
	s_sleep 8
	s_cbranch_scc0 .LBB0_903
	global_load_dword v17, v16, s[4:5] sc1
	s_waitcnt vmcnt(0)
	v_cmp_eq_u32_e32 vcc, 0, v17
	s_cbranch_vccnz .LBB0_905
	s_mov_b64 s[64:65], 0

.LBB0_917:
	s_and_b32 s12, s3, 0xff
	s_mov_b64 s[30:31], -1
	s_cmp_lg_u32 s12, 0
	s_mov_b64 s[38:39], -1
	s_sleep 8
	s_cbranch_scc1 .LBB0_920
	global_load_dword v2, v0, s[10:11] sc1
	s_waitcnt vmcnt(0)
	v_cmp_eq_u32_e32 vcc, 0, v2
	s_cbranch_vccnz .LBB0_922
	s_mov_b64 s[38:39], 0
	s_mov_b64 s[36:37], -1

.LBB0_934:
	s_and_b32 s12, s3, 0xff
	s_cmp_lg_u32 s12, 0
	s_mov_b64 s[36:37], -1
	s_sleep 8
	s_cbranch_scc1 .LBB0_937
	global_load_dword v1, v0, s[10:11] sc1
	s_waitcnt vmcnt(0)
	v_cmp_eq_u32_e32 vcc, 0, v1
	s_cbranch_vccnz .LBB0_939
	s_mov_b64 s[36:37], 0
	s_mov_b64 s[30:31], -1

.LBB0_1351:
	global_load_dword v15, v16, s[6:7] sc1
	s_waitcnt lgkmcnt(0)
	global_load_dword v0, v16, s[10:11] sc1
	global_load_dword v1, v16, s[22:23] sc1
	global_load_dword v2, v16, s[26:27] sc1
	global_load_dword v3, v16, s[28:29] sc1
	global_load_dword v4, v16, s[30:31] sc1
	global_load_dword v5, v16, s[36:37] sc1
	global_load_dword v6, v16, s[38:39] sc1
	global_load_dword v7, v16, s[40:41] sc1
	global_load_dword v8, v16, s[42:43] sc1
	global_load_dword v9, v16, s[48:49] sc1
	global_load_dword v10, v16, s[50:51] sc1
	global_load_dword v11, v16, s[52:53] sc1
	global_load_dword v12, v16, s[54:55] sc1
	global_load_dword v13, v16, s[56:57] sc1
	global_load_dword v14, v16, s[58:59] sc1
	s_mov_b64 s[62:63], -1
	s_mov_b64 s[64:65], -1
	s_waitcnt vmcnt(14)
	v_add_u32_e32 v17, v0, v15
	s_waitcnt vmcnt(13)
	v_add_u32_e32 v17, v17, v1
	s_waitcnt vmcnt(12)
	v_add_u32_e32 v17, v17, v2
	s_waitcnt vmcnt(11)
	v_add_u32_e32 v17, v17, v3
	s_waitcnt vmcnt(10)
	v_add_u32_e32 v17, v17, v4
	s_waitcnt vmcnt(9)
	v_add_u32_e32 v17, v17, v5
	s_waitcnt vmcnt(8)
	v_add_u32_e32 v17, v17, v6
	s_waitcnt vmcnt(7)
	v_add_u32_e32 v17, v17, v7
	s_waitcnt vmcnt(6)
	v_add_u32_e32 v17, v17, v8
	s_waitcnt vmcnt(5)
	v_add_u32_e32 v17, v17, v9
	s_waitcnt vmcnt(4)
	v_add_u32_e32 v17, v17, v10
	s_waitcnt vmcnt(3)
	v_add_u32_e32 v17, v17, v11
	s_waitcnt vmcnt(2)
	v_add_u32_e32 v17, v17, v12
	s_waitcnt vmcnt(1)
	v_add_u32_e32 v17, v17, v13
	s_waitcnt vmcnt(0)
	v_add_u32_e32 v17, v17, v14
	v_cmp_eq_u32_e32 vcc, s3, v17
	s_cbranch_vccnz .LBB0_1350
	s_and_b32 s13, s12, 0xff
	s_cmp_eq_u32 s13, 0
	s_mov_b64 s[66:67], -1
	s_sleep 8
	s_cbranch_scc0 .LBB0_1355
	global_load_dword v17, v16, s[4:5] sc1
	s_waitcnt vmcnt(0)
	v_cmp_eq_u32_e32 vcc, 0, v17
	s_cbranch_vccnz .LBB0_1357
	s_mov_b64 s[66:67], 0

.LBB0_1369:
	s_and_b32 s12, s3, 0xff
	s_mov_b64 s[36:37], -1
	s_cmp_lg_u32 s12, 0
	s_mov_b64 s[40:41], -1
	s_sleep 8
	s_cbranch_scc1 .LBB0_1372
	global_load_dword v2, v0, s[22:23] sc1
	s_waitcnt vmcnt(0)
	v_cmp_eq_u32_e32 vcc, 0, v2
	s_cbranch_vccnz .LBB0_1374
	s_mov_b64 s[40:41], 0
	s_mov_b64 s[38:39], -1

.LBB0_1386:
	s_and_b32 s12, s3, 0xff
	s_cmp_lg_u32 s12, 0
	s_mov_b64 s[38:39], -1
	s_sleep 8
	s_cbranch_scc1 .LBB0_1389
	global_load_dword v1, v0, s[22:23] sc1
	s_waitcnt vmcnt(0)
	v_cmp_eq_u32_e32 vcc, 0, v1
	s_cbranch_vccnz .LBB0_1391
	s_mov_b64 s[38:39], 0
	s_mov_b64 s[36:37], -1

.LBB0_1425:
	global_load_dword v15, v16, s[6:7] sc1
	s_waitcnt lgkmcnt(0)
	global_load_dword v0, v16, s[10:11] sc1
	global_load_dword v1, v16, s[22:23] sc1
	global_load_dword v2, v16, s[26:27] sc1
	global_load_dword v3, v16, s[28:29] sc1
	global_load_dword v4, v16, s[30:31] sc1
	global_load_dword v5, v16, s[36:37] sc1
	global_load_dword v6, v16, s[38:39] sc1
	global_load_dword v7, v16, s[40:41] sc1
	global_load_dword v8, v16, s[42:43] sc1
	global_load_dword v9, v16, s[48:49] sc1
	global_load_dword v10, v16, s[50:51] sc1
	global_load_dword v11, v16, s[52:53] sc1
	global_load_dword v12, v16, s[54:55] sc1
	global_load_dword v13, v16, s[56:57] sc1
	global_load_dword v14, v16, s[58:59] sc1
	s_mov_b64 s[60:61], -1
	s_mov_b64 s[62:63], -1
	s_waitcnt vmcnt(14)
	v_add_u32_e32 v17, v0, v15
	s_waitcnt vmcnt(13)
	v_add_u32_e32 v17, v17, v1
	s_waitcnt vmcnt(12)
	v_add_u32_e32 v17, v17, v2
	s_waitcnt vmcnt(11)
	v_add_u32_e32 v17, v17, v3
	s_waitcnt vmcnt(10)
	v_add_u32_e32 v17, v17, v4
	s_waitcnt vmcnt(9)
	v_add_u32_e32 v17, v17, v5
	s_waitcnt vmcnt(8)
	v_add_u32_e32 v17, v17, v6
	s_waitcnt vmcnt(7)
	v_add_u32_e32 v17, v17, v7
	s_waitcnt vmcnt(6)
	v_add_u32_e32 v17, v17, v8
	s_waitcnt vmcnt(5)
	v_add_u32_e32 v17, v17, v9
	s_waitcnt vmcnt(4)
	v_add_u32_e32 v17, v17, v10
	s_waitcnt vmcnt(3)
	v_add_u32_e32 v17, v17, v11
	s_waitcnt vmcnt(2)
	v_add_u32_e32 v17, v17, v12
	s_waitcnt vmcnt(1)
	v_add_u32_e32 v17, v17, v13
	s_waitcnt vmcnt(0)
	v_add_u32_e32 v17, v17, v14
	v_cmp_eq_u32_e32 vcc, s3, v17
	s_cbranch_vccnz .LBB0_1424
	s_and_b32 s13, s12, 0xff
	s_cmp_eq_u32 s13, 0
	s_mov_b64 s[64:65], -1
	s_sleep 8
	s_cbranch_scc0 .LBB0_1429
	global_load_dword v17, v16, s[4:5] sc1
	s_waitcnt vmcnt(0)
	v_cmp_eq_u32_e32 vcc, 0, v17
	s_cbranch_vccnz .LBB0_1431
	s_mov_b64 s[64:65], 0

.LBB0_1487:
	global_load_dword v15, v16, s[6:7] sc1
	s_waitcnt lgkmcnt(0)
	global_load_dword v0, v16, s[8:9] sc1
	global_load_dword v1, v16, s[10:11] sc1
	global_load_dword v2, v16, s[22:23] sc1
	global_load_dword v3, v16, s[26:27] sc1
	global_load_dword v4, v16, s[28:29] sc1
	global_load_dword v5, v16, s[30:31] sc1
	global_load_dword v6, v16, s[36:37] sc1
	global_load_dword v7, v16, s[38:39] sc1
	global_load_dword v8, v16, s[40:41] sc1
	global_load_dword v9, v16, s[42:43] sc1
	global_load_dword v10, v16, s[44:45] sc1
	global_load_dword v11, v16, s[46:47] sc1
	global_load_dword v12, v16, s[48:49] sc1
	global_load_dword v13, v16, s[50:51] sc1
	global_load_dword v14, v16, s[52:53] sc1
	s_mov_b64 s[54:55], -1
	s_mov_b64 s[56:57], -1
	s_waitcnt vmcnt(14)
	v_add_u32_e32 v17, v0, v15
	s_waitcnt vmcnt(13)
	v_add_u32_e32 v17, v17, v1
	s_waitcnt vmcnt(12)
	v_add_u32_e32 v17, v17, v2
	s_waitcnt vmcnt(11)
	v_add_u32_e32 v17, v17, v3
	s_waitcnt vmcnt(10)
	v_add_u32_e32 v17, v17, v4
	s_waitcnt vmcnt(9)
	v_add_u32_e32 v17, v17, v5
	s_waitcnt vmcnt(8)
	v_add_u32_e32 v17, v17, v6
	s_waitcnt vmcnt(7)
	v_add_u32_e32 v17, v17, v7
	s_waitcnt vmcnt(6)
	v_add_u32_e32 v17, v17, v8
	s_waitcnt vmcnt(5)
	v_add_u32_e32 v17, v17, v9
	s_waitcnt vmcnt(4)
	v_add_u32_e32 v17, v17, v10
	s_waitcnt vmcnt(3)
	v_add_u32_e32 v17, v17, v11
	s_waitcnt vmcnt(2)
	v_add_u32_e32 v17, v17, v12
	s_waitcnt vmcnt(1)
	v_add_u32_e32 v17, v17, v13
	s_waitcnt vmcnt(0)
	v_add_u32_e32 v17, v17, v14
	v_cmp_eq_u32_e32 vcc, s3, v17
	s_cbranch_vccnz .LBB0_1486
	s_and_b32 s13, s12, 0xff
	s_cmp_eq_u32 s13, 0
	s_mov_b64 s[58:59], -1
	s_sleep 8
	s_cbranch_scc0 .LBB0_1491
	global_load_dword v17, v16, s[4:5] sc1
	s_waitcnt vmcnt(0)
	v_cmp_eq_u32_e32 vcc, 0, v17
	s_cbranch_vccnz .LBB0_1493
	s_mov_b64 s[58:59], 0

.LBB0_1931:
	global_load_dword v15, v16, s[6:7] sc1
	s_waitcnt lgkmcnt(0)
	global_load_dword v0, v16, s[8:9] sc1
	global_load_dword v1, v16, s[10:11] sc1
	global_load_dword v2, v16, s[22:23] sc1
	global_load_dword v3, v16, s[24:25] sc1
	global_load_dword v4, v16, s[26:27] sc1
	global_load_dword v5, v16, s[28:29] sc1
	global_load_dword v6, v16, s[30:31] sc1
	global_load_dword v7, v16, s[36:37] sc1
	global_load_dword v8, v16, s[38:39] sc1
	global_load_dword v9, v16, s[40:41] sc1
	global_load_dword v10, v16, s[42:43] sc1
	global_load_dword v11, v16, s[44:45] sc1
	global_load_dword v12, v16, s[46:47] sc1
	global_load_dword v13, v16, s[48:49] sc1
	global_load_dword v14, v16, s[50:51] sc1
	s_mov_b64 s[52:53], -1
	s_mov_b64 s[54:55], -1
	s_waitcnt vmcnt(14)
	v_add_u32_e32 v17, v0, v15
	s_waitcnt vmcnt(13)
	v_add_u32_e32 v17, v17, v1
	s_waitcnt vmcnt(12)
	v_add_u32_e32 v17, v17, v2
	s_waitcnt vmcnt(11)
	v_add_u32_e32 v17, v17, v3
	s_waitcnt vmcnt(10)
	v_add_u32_e32 v17, v17, v4
	s_waitcnt vmcnt(9)
	v_add_u32_e32 v17, v17, v5
	s_waitcnt vmcnt(8)
	v_add_u32_e32 v17, v17, v6
	s_waitcnt vmcnt(7)
	v_add_u32_e32 v17, v17, v7
	s_waitcnt vmcnt(6)
	v_add_u32_e32 v17, v17, v8
	s_waitcnt vmcnt(5)
	v_add_u32_e32 v17, v17, v9
	s_waitcnt vmcnt(4)
	v_add_u32_e32 v17, v17, v10
	s_waitcnt vmcnt(3)
	v_add_u32_e32 v17, v17, v11
	s_waitcnt vmcnt(2)
	v_add_u32_e32 v17, v17, v12
	s_waitcnt vmcnt(1)
	v_add_u32_e32 v17, v17, v13
	s_waitcnt vmcnt(0)
	v_add_u32_e32 v17, v17, v14
	v_cmp_eq_u32_e32 vcc, s3, v17
	s_cbranch_vccnz .LBB0_1930
	s_and_b32 s13, s12, 0xff
	s_cmp_eq_u32 s13, 0
	s_mov_b64 s[56:57], -1
	s_sleep 8
	s_cbranch_scc0 .LBB0_1935
	global_load_dword v17, v16, s[4:5] sc1
	s_waitcnt vmcnt(0)
	v_cmp_eq_u32_e32 vcc, 0, v17
	s_cbranch_vccnz .LBB0_1937
	s_mov_b64 s[56:57], 0

.LBB0_1949:
	s_and_b32 s12, s3, 0xff
	s_mov_b64 s[28:29], -1
	s_cmp_lg_u32 s12, 0
	s_mov_b64 s[36:37], -1
	s_sleep 8
	s_cbranch_scc1 .LBB0_1952
	global_load_dword v2, v0, s[10:11] sc1
	s_waitcnt vmcnt(0)
	v_cmp_eq_u32_e32 vcc, 0, v2
	s_cbranch_vccnz .LBB0_1954
	s_mov_b64 s[36:37], 0
	s_mov_b64 s[30:31], -1

.LBB0_1966:
	s_and_b32 s12, s3, 0xff
	s_cmp_lg_u32 s12, 0
	s_mov_b64 s[30:31], -1
	s_sleep 8
	s_cbranch_scc1 .LBB0_1969
	global_load_dword v1, v0, s[10:11] sc1
	s_waitcnt vmcnt(0)
	v_cmp_eq_u32_e32 vcc, 0, v1
	s_cbranch_vccnz .LBB0_1971
	s_mov_b64 s[30:31], 0
	s_mov_b64 s[28:29], -1

.LBB0_2028:
	global_load_dword v15, v16, s[6:7] sc1
	s_waitcnt lgkmcnt(0)
	global_load_dword v0, v16, s[8:9] sc1
	global_load_dword v1, v16, s[10:11] sc1
	global_load_dword v2, v16, s[20:21] sc1
	global_load_dword v3, v16, s[22:23] sc1
	global_load_dword v4, v16, s[24:25] sc1
	global_load_dword v5, v16, s[26:27] sc1
	global_load_dword v6, v16, s[28:29] sc1
	global_load_dword v7, v16, s[30:31] sc1
	global_load_dword v8, v16, s[36:37] sc1
	global_load_dword v9, v16, s[38:39] sc1
	global_load_dword v10, v16, s[40:41] sc1
	global_load_dword v11, v16, s[42:43] sc1
	global_load_dword v12, v16, s[44:45] sc1
	global_load_dword v13, v16, s[46:47] sc1
	global_load_dword v14, v16, s[48:49] sc1
	s_mov_b64 s[50:51], -1
	s_mov_b64 s[52:53], -1
	s_waitcnt vmcnt(14)
	v_add_u32_e32 v17, v0, v15
	s_waitcnt vmcnt(13)
	v_add_u32_e32 v17, v17, v1
	s_waitcnt vmcnt(12)
	v_add_u32_e32 v17, v17, v2
	s_waitcnt vmcnt(11)
	v_add_u32_e32 v17, v17, v3
	s_waitcnt vmcnt(10)
	v_add_u32_e32 v17, v17, v4
	s_waitcnt vmcnt(9)
	v_add_u32_e32 v17, v17, v5
	s_waitcnt vmcnt(8)
	v_add_u32_e32 v17, v17, v6
	s_waitcnt vmcnt(7)
	v_add_u32_e32 v17, v17, v7
	s_waitcnt vmcnt(6)
	v_add_u32_e32 v17, v17, v8
	s_waitcnt vmcnt(5)
	v_add_u32_e32 v17, v17, v9
	s_waitcnt vmcnt(4)
	v_add_u32_e32 v17, v17, v10
	s_waitcnt vmcnt(3)
	v_add_u32_e32 v17, v17, v11
	s_waitcnt vmcnt(2)
	v_add_u32_e32 v17, v17, v12
	s_waitcnt vmcnt(1)
	v_add_u32_e32 v17, v17, v13
	s_waitcnt vmcnt(0)
	v_add_u32_e32 v17, v17, v14
	v_cmp_eq_u32_e32 vcc, s3, v17
	s_cbranch_vccnz .LBB0_2027
	s_and_b32 s13, s12, 0xff
	s_cmp_eq_u32 s13, 0
	s_mov_b64 s[54:55], -1
	s_sleep 8
	s_cbranch_scc0 .LBB0_2032
	global_load_dword v17, v16, s[4:5] sc1
	s_waitcnt vmcnt(0)
	v_cmp_eq_u32_e32 vcc, 0, v17
	s_cbranch_vccnz .LBB0_2034
	s_mov_b64 s[54:55], 0

.LBB0_2046:
	s_and_b32 s12, s3, 0xff
	s_mov_b64 s[26:27], -1
	s_cmp_lg_u32 s12, 0
	s_mov_b64 s[30:31], -1
	s_sleep 8
	s_cbranch_scc1 .LBB0_2049
	global_load_dword v2, v0, s[10:11] sc1
	s_waitcnt vmcnt(0)
	v_cmp_eq_u32_e32 vcc, 0, v2
	s_cbranch_vccnz .LBB0_2051
	s_mov_b64 s[30:31], 0
	s_mov_b64 s[28:29], -1

.LBB0_2063:
	s_and_b32 s12, s3, 0xff
	s_cmp_lg_u32 s12, 0
	s_mov_b64 s[28:29], -1
	s_sleep 8
	s_cbranch_scc1 .LBB0_2066
	global_load_dword v1, v0, s[10:11] sc1
	s_waitcnt vmcnt(0)
	v_cmp_eq_u32_e32 vcc, 0, v1
	s_cbranch_vccnz .LBB0_2068
	s_mov_b64 s[28:29], 0
	s_mov_b64 s[26:27], -1

.LBB0_2103:
	global_load_dword v15, v16, s[6:7] sc1
	s_waitcnt lgkmcnt(0)
	global_load_dword v0, v16, s[8:9] sc1
	global_load_dword v1, v16, s[10:11] sc1
	global_load_dword v2, v16, s[18:19] sc1
	global_load_dword v3, v16, s[20:21] sc1
	global_load_dword v4, v16, s[22:23] sc1
	global_load_dword v5, v16, s[24:25] sc1
	global_load_dword v6, v16, s[26:27] sc1
	global_load_dword v7, v16, s[28:29] sc1
	global_load_dword v8, v16, s[30:31] sc1
	global_load_dword v9, v16, s[36:37] sc1
	global_load_dword v10, v16, s[38:39] sc1
	global_load_dword v11, v16, s[40:41] sc1
	global_load_dword v12, v16, s[42:43] sc1
	global_load_dword v13, v16, s[44:45] sc1
	global_load_dword v14, v16, s[46:47] sc1
	s_mov_b64 s[48:49], -1
	s_mov_b64 s[50:51], -1
	s_waitcnt vmcnt(14)
	v_add_u32_e32 v17, v0, v15
	s_waitcnt vmcnt(13)
	v_add_u32_e32 v17, v17, v1
	s_waitcnt vmcnt(12)
	v_add_u32_e32 v17, v17, v2
	s_waitcnt vmcnt(11)
	v_add_u32_e32 v17, v17, v3
	s_waitcnt vmcnt(10)
	v_add_u32_e32 v17, v17, v4
	s_waitcnt vmcnt(9)
	v_add_u32_e32 v17, v17, v5
	s_waitcnt vmcnt(8)
	v_add_u32_e32 v17, v17, v6
	s_waitcnt vmcnt(7)
	v_add_u32_e32 v17, v17, v7
	s_waitcnt vmcnt(6)
	v_add_u32_e32 v17, v17, v8
	s_waitcnt vmcnt(5)
	v_add_u32_e32 v17, v17, v9
	s_waitcnt vmcnt(4)
	v_add_u32_e32 v17, v17, v10
	s_waitcnt vmcnt(3)
	v_add_u32_e32 v17, v17, v11
	s_waitcnt vmcnt(2)
	v_add_u32_e32 v17, v17, v12
	s_waitcnt vmcnt(1)
	v_add_u32_e32 v17, v17, v13
	s_waitcnt vmcnt(0)
	v_add_u32_e32 v17, v17, v14
	v_cmp_eq_u32_e32 vcc, s3, v17
	s_cbranch_vccnz .LBB0_2102
	s_and_b32 s13, s12, 0xff
	s_cmp_eq_u32 s13, 0
	s_mov_b64 s[52:53], -1
	s_sleep 8
	s_cbranch_scc0 .LBB0_2107
	global_load_dword v17, v16, s[4:5] sc1
	s_waitcnt vmcnt(0)
	v_cmp_eq_u32_e32 vcc, 0, v17
	s_cbranch_vccnz .LBB0_2109
	s_mov_b64 s[52:53], 0

.LBB0_2121:
	s_and_b32 s12, s3, 0xff
	s_mov_b64 s[24:25], -1
	s_cmp_lg_u32 s12, 0
	s_mov_b64 s[28:29], -1
	s_sleep 8
	s_cbranch_scc1 .LBB0_2124
	global_load_dword v2, v0, s[10:11] sc1
	s_waitcnt vmcnt(0)
	v_cmp_eq_u32_e32 vcc, 0, v2
	s_cbranch_vccnz .LBB0_2126
	s_mov_b64 s[28:29], 0
	s_mov_b64 s[26:27], -1

.LBB0_2138:
	s_and_b32 s12, s3, 0xff
	s_cmp_lg_u32 s12, 0
	s_mov_b64 s[26:27], -1
	s_sleep 8
	s_cbranch_scc1 .LBB0_2141
	global_load_dword v1, v0, s[10:11] sc1
	s_waitcnt vmcnt(0)
	v_cmp_eq_u32_e32 vcc, 0, v1
	s_cbranch_vccnz .LBB0_2143
	s_mov_b64 s[26:27], 0
	s_mov_b64 s[24:25], -1

.LBB0_2186:
	global_load_dword v15, v16, s[4:5] sc1
	s_waitcnt lgkmcnt(0)
	global_load_dword v0, v16, s[6:7] sc1
	global_load_dword v1, v16, s[8:9] sc1
	global_load_dword v2, v16, s[10:11] sc1
	global_load_dword v3, v16, s[12:13] sc1
	global_load_dword v4, v16, s[14:15] sc1
	global_load_dword v5, v16, s[16:17] sc1
	global_load_dword v6, v16, s[18:19] sc1
	global_load_dword v7, v16, s[20:21] sc1
	global_load_dword v8, v16, s[22:23] sc1
	global_load_dword v9, v16, s[24:25] sc1
	global_load_dword v10, v16, s[26:27] sc1
	global_load_dword v11, v16, s[28:29] sc1
	global_load_dword v12, v16, s[30:31] sc1
	global_load_dword v13, v16, s[36:37] sc1
	global_load_dword v14, v16, s[38:39] sc1
	s_mov_b64 s[40:41], -1
	s_mov_b64 s[42:43], -1
	s_waitcnt vmcnt(14)
	v_add_u32_e32 v17, v0, v15
	s_waitcnt vmcnt(13)
	v_add_u32_e32 v17, v17, v1
	s_waitcnt vmcnt(12)
	v_add_u32_e32 v17, v17, v2
	s_waitcnt vmcnt(11)
	v_add_u32_e32 v17, v17, v3
	s_waitcnt vmcnt(10)
	v_add_u32_e32 v17, v17, v4
	s_waitcnt vmcnt(9)
	v_add_u32_e32 v17, v17, v5
	s_waitcnt vmcnt(8)
	v_add_u32_e32 v17, v17, v6
	s_waitcnt vmcnt(7)
	v_add_u32_e32 v17, v17, v7
	s_waitcnt vmcnt(6)
	v_add_u32_e32 v17, v17, v8
	s_waitcnt vmcnt(5)
	v_add_u32_e32 v17, v17, v9
	s_waitcnt vmcnt(4)
	v_add_u32_e32 v17, v17, v10
	s_waitcnt vmcnt(3)
	v_add_u32_e32 v17, v17, v11
	s_waitcnt vmcnt(2)
	v_add_u32_e32 v17, v17, v12
	s_waitcnt vmcnt(1)
	v_add_u32_e32 v17, v17, v13
	s_waitcnt vmcnt(0)
	v_add_u32_e32 v17, v17, v14
	v_cmp_eq_u32_e32 vcc, s34, v17
	s_cbranch_vccnz .LBB0_2185
	s_and_b32 s40, s35, 0xff
	s_cmp_eq_u32 s40, 0
	s_mov_b64 s[40:41], -1
	s_mov_b64 s[44:45], -1
	s_sleep 8
	s_cbranch_scc0 .LBB0_2190
	global_load_dword v17, v16, s[2:3] sc1
	s_waitcnt vmcnt(0)
	v_cmp_eq_u32_e32 vcc, 0, v17
	s_cbranch_vccnz .LBB0_2192
	s_mov_b64 s[44:45], 0

.LBB0_2204:
	s_and_b32 s18, s22, 0xff
	s_mov_b64 s[16:17], -1
	s_cmp_lg_u32 s18, 0
	s_mov_b64 s[20:21], -1
	s_sleep 8
	s_cbranch_scc1 .LBB0_2207
	global_load_dword v2, v0, s[8:9] sc1
	s_waitcnt vmcnt(0)
	v_cmp_eq_u32_e32 vcc, 0, v2
	s_cbranch_vccnz .LBB0_2209
	s_mov_b64 s[20:21], 0
	s_mov_b64 s[18:19], -1

.LBB0_2221:
	s_and_b32 s16, s22, 0xff
	s_cmp_lg_u32 s16, 0
	s_mov_b64 s[18:19], -1
	s_sleep 8
	s_cbranch_scc1 .LBB0_2224
	global_load_dword v1, v0, s[8:9] sc1
	s_waitcnt vmcnt(0)
	v_cmp_eq_u32_e32 vcc, 0, v1
	s_cbranch_vccnz .LBB0_2226
	s_mov_b64 s[18:19], 0
	s_mov_b64 s[16:17], -1
